# v27 with the s_sleep removed from the 13 grid-barrier poll loops (back-to-back sc1 polls)
# baseline (speedup 1.0000x reference)
; __device__ __forceinline__ unsigned xb_ld(unsigned* p)              { return __hip_atomic_load(p, __ATOMIC_RELAXED, __HIP_MEMORY_SCOPE_AGENT); }
; __device__ __forceinline__ unsigned xb_add(unsigned* p, unsigned v) { return __hip_atomic_fetch_add(p, v, __ATOMIC_RELAXED, __HIP_MEMORY_SCOPE_AGENT); }
; #define XB_SPIN(cond, bar) do { unsigned _sp = 0; while (cond) { __builtin_amdgcn_s_sleep(1); \
;     if ((++_sp & 255u) == 0u) { if (xb_ld(&(bar)[XB_TMO])) break; if (_sp > XB_SPIN_CAP) { atomicAdd(&(bar)[XB_TMO], 1u); break; } } } } while (0)
; __device__ __forceinline__ void xcd_barrier(const XcdBarrier& b, bool t0) {
;     ...
;             else XB_SPIN(xb_ld(&bar[XB_TOPGEN]) == tg, bar);
;             __builtin_amdgcn_fence(__ATOMIC_ACQUIRE, "agent");
;             xb_add(&bar[XB_XGEN(b.x)], 1u);
;             asm volatile("s_waitcnt vmcnt(0)" ::: "memory");
;         } else {
;             XB_SPIN(xb_ld(&bar[XB_XGEN(b.x)]) == gen, bar);
.Lgs0_spin:
	global_load_dword v3, v4, s[2:3] offset:1024 sc1
	s_waitcnt vmcnt(0)
	v_readfirstlane_b32 s5, v3
	s_cmp_ge_u32 s5, s8
	s_cbranch_scc1 .Lgs0_done
	s_add_u32 s4, s4, 1
	s_cmp_lt_u32 s4, 0x40000
	s_cbranch_scc1 .Lgs0_spin

; __device__ __forceinline__ unsigned xb_ld(unsigned* p)              { return __hip_atomic_load(p, __ATOMIC_RELAXED, __HIP_MEMORY_SCOPE_AGENT); }
; #define XB_SPIN(cond, bar) do { unsigned _sp = 0; while (cond) { __builtin_amdgcn_s_sleep(1); \
;     if ((++_sp & 255u) == 0u) { if (xb_ld(&(bar)[XB_TMO])) break; if (_sp > XB_SPIN_CAP) { atomicAdd(&(bar)[XB_TMO], 1u); break; } } } } while (0)
; __device__ __forceinline__ void xcd_barrier(const XcdBarrier& b, bool t0) {
;     ...
;             XB_SPIN(xb_ld(&bar[XB_XGEN(b.x)]) == gen, bar);
.Lgs10_spin:
	global_load_dword v3, v4, s[2:3] offset:1024 sc1
	s_waitcnt vmcnt(0)
	v_readfirstlane_b32 s7, v3
	s_cmp_ge_u32 s7, s10
	s_cbranch_scc1 .Lgs10_done
	s_add_u32 s6, s6, 1
	s_cmp_lt_u32 s6, 0x40000
	s_cbranch_scc1 .Lgs10_spin
